# recurrence output stores non-temporal
# baseline (speedup 1.0000x reference)
.LBB0_1293:
	s_add_i32 s8, s10, -1
	s_and_b32 s8, s8, 1
	s_lshl_b32 s9, s8, 11
	s_add_i32 s11, s9, 0
	s_add_i32 s11, s11, 0x1e400
	v_add_u32_e32 v147, s11, v136
	ds_read_b128 v[150:153], v147
	ds_read_b128 v[154:157], v147 offset:16
	s_mulk_i32 s8, 0x4400
	v_add_u32_e32 v147, s8, v135
	v_add_u32_e32 v177, s11, v133
	s_waitcnt lgkmcnt(1)
	v_mov_b32_e32 v158, v150
	s_waitcnt lgkmcnt(0)
	v_mov_b32_e32 v159, v154
	v_mov_b32_e32 v154, v151
	v_add_u32_e32 v150, v147, v134
	v_pk_add_f32 v[154:155], v[158:159], v[154:155]
	v_mov_b32_e32 v158, v152
	v_mov_b32_e32 v159, v156
	v_mov_b32_e32 v156, v153
	ds_read_b128 v[150:153], v150
	v_pk_add_f32 v[156:157], v[158:159], v[156:157]
	s_mov_b32 s22, 0x358637bd
	v_pk_add_f32 v[158:159], v[154:155], v[156:157]
	ds_read_b128 v[154:157], v177
	s_waitcnt lgkmcnt(1)
	v_lshlrev_b32_e32 v162, 16, v150
	v_and_b32_e32 v163, 0xffff0000, v150
	v_lshlrev_b32_e32 v166, 16, v151
	v_and_b32_e32 v167, 0xffff0000, v151
	v_lshlrev_b32_e32 v170, 16, v152
	v_and_b32_e32 v171, 0xffff0000, v152
	v_lshlrev_b32_e32 v174, 16, v153
	v_and_b32_e32 v175, 0xffff0000, v153
	ds_read_b128 v[150:153], v177 offset:16
	s_waitcnt lgkmcnt(1)
	v_mov_b32_e32 v178, v154
	v_mov_b32_e32 v154, v156
	s_add_u32 s8, s2, s18
	s_addc_u32 s9, s3, 0
	s_waitcnt lgkmcnt(0)
	v_mov_b32_e32 v179, v150
	v_mov_b32_e32 v150, v155
	v_mov_b32_e32 v155, v152
	v_mov_b32_e32 v152, v157
	v_pk_add_f32 v[150:151], v[178:179], v[150:151]
	v_pk_add_f32 v[152:153], v[154:155], v[152:153]
	v_mov_b64_e32 v[154:155], s[22:23]
	v_pk_add_f32 v[150:151], v[150:151], v[152:153]
	v_mov_b32_e32 v153, v158
	v_mov_b32_e32 v152, v150
	v_mov_b32_e32 v158, v151
	v_pk_add_f32 v[150:151], v[152:153], v[158:159]
	s_brev_b32 s22, 60
	v_pk_fma_f32 v[156:157], v[150:151], s[22:23], v[154:155] op_sel_hi:[1,0,0]
	s_waitcnt vmcnt(17)
	v_lshlrev_b32_e32 v164, 16, v82
	v_and_b32_e32 v165, 0xffff0000, v82
	v_lshlrev_b32_e32 v168, 16, v83
	v_mov_b32_e32 v150, v157
	v_rsq_f32_e32 v152, v150
	v_lshl_add_u64 v[150:151], s[8:9], 0, v[92:93]
	v_lshlrev_b64 v[150:151], 11, v[150:151]
	v_lshl_add_u64 v[158:159], v[110:111], 0, v[150:151]
	s_nop 0
	v_mov_b32_e32 v178, v152
	v_pk_mul_f32 v[150:151], v[178:179], v[162:163] op_sel_hi:[0,1]
	v_pk_mul_f32 v[152:153], v[178:179], v[166:167] op_sel_hi:[0,1]
	v_and_b32_e32 v169, 0xffff0000, v83
	v_pk_mul_f32 v[150:151], v[6:7], v[150:151]
	v_pk_mul_f32 v[152:153], v[8:9], v[152:153]
	v_pk_mul_f32 v[150:151], v[150:151], v[164:165]
	v_pk_mul_f32 v[152:153], v[152:153], v[168:169]
	v_cvt_pk_bf16_f32 v150, v150, v151
	v_cvt_pk_bf16_f32 v151, v152, v153
	v_pk_mul_f32 v[152:153], v[178:179], v[170:171] op_sel_hi:[0,1]
	v_lshlrev_b32_e32 v172, 16, v84
	v_and_b32_e32 v173, 0xffff0000, v84
	v_pk_mul_f32 v[152:153], v[2:3], v[152:153]
	v_pk_mul_f32 v[152:153], v[152:153], v[172:173]
	v_add_u32_e32 v82, v147, v132
	v_cvt_pk_bf16_f32 v152, v152, v153
	v_mov_b32_e32 v153, v156
	v_lshlrev_b32_e32 v176, 16, v85
	v_and_b32_e32 v177, 0xffff0000, v85
	ds_read_b128 v[82:85], v82
	v_pk_mul_f32 v[162:163], v[178:179], v[174:175] op_sel_hi:[0,1]
	v_rsq_f32_e32 v164, v153
	v_pk_mul_f32 v[162:163], v[4:5], v[162:163]
	v_add_u32_e32 v171, s11, v103
	v_pk_mul_f32 v[156:157], v[162:163], v[176:177]
	s_waitcnt vmcnt(15)
	v_lshlrev_b32_e32 v162, 16, v15
	v_cvt_pk_bf16_f32 v153, v156, v157
	global_store_dwordx4 v[158:159], v[150:153], off nt
	v_lshlrev_b32_e32 v156, 16, v66
	v_and_b32_e32 v157, 0xffff0000, v66
	s_nop 0
	v_mov_b32_e32 v150, v164
	s_waitcnt lgkmcnt(0)
	v_lshlrev_b32_e32 v152, 16, v82
	v_and_b32_e32 v153, 0xffff0000, v82
	v_pk_mul_f32 v[152:153], v[150:151], v[152:153] op_sel_hi:[0,1]
	v_pk_mul_f32 v[152:153], v[6:7], v[152:153]
	v_lshlrev_b32_e32 v82, 16, v83
	v_and_b32_e32 v83, 0xffff0000, v83
	v_pk_mul_f32 v[152:153], v[152:153], v[156:157]
	v_pk_mul_f32 v[82:83], v[150:151], v[82:83] op_sel_hi:[0,1]
	v_cvt_pk_bf16_f32 v66, v152, v153
	v_pk_mul_f32 v[82:83], v[8:9], v[82:83]
	v_lshlrev_b32_e32 v152, 16, v67
	v_and_b32_e32 v153, 0xffff0000, v67
	v_pk_mul_f32 v[82:83], v[82:83], v[152:153]
	v_lshlrev_b32_e32 v152, 16, v68
	v_cvt_pk_bf16_f32 v67, v82, v83
	v_lshlrev_b32_e32 v82, 16, v84
	v_and_b32_e32 v83, 0xffff0000, v84
	v_pk_mul_f32 v[82:83], v[150:151], v[82:83] op_sel_hi:[0,1]
	v_pk_mul_f32 v[82:83], v[2:3], v[82:83]
	v_and_b32_e32 v153, 0xffff0000, v68
	v_pk_mul_f32 v[82:83], v[82:83], v[152:153]
	v_lshlrev_b32_e32 v84, 16, v69
	v_cvt_pk_bf16_f32 v68, v82, v83
	v_lshlrev_b32_e32 v82, 16, v85
	v_and_b32_e32 v83, 0xffff0000, v85
	v_pk_mul_f32 v[82:83], v[150:151], v[82:83] op_sel_hi:[0,1]
	v_pk_mul_f32 v[82:83], v[4:5], v[82:83]
	v_and_b32_e32 v85, 0xffff0000, v69
	v_pk_mul_f32 v[82:83], v[82:83], v[84:85]
	v_add_u32_e32 v150, s11, v107
	v_cvt_pk_bf16_f32 v69, v82, v83
	ds_read_b128 v[82:85], v150
	ds_read_b128 v[150:153], v150 offset:16
	v_lshl_add_u64 v[156:157], s[8:9], 0, v[90:91]
	v_lshlrev_b64 v[156:157], 11, v[156:157]
	v_lshl_add_u64 v[156:157], v[110:111], 0, v[156:157]
	global_store_dwordx4 v[156:157], v[66:69], off nt
	v_lshlrev_b32_e32 v156, 16, v14
	v_and_b32_e32 v157, 0xffff0000, v14
	s_waitcnt lgkmcnt(1)
; #define LBAR() do { asm volatile("s_waitcnt lgkmcnt(0)" ::: "memory"); __builtin_amdgcn_s_barrier(); asm volatile("" ::: "memory"); } while (0)
; #define GATE_LOAD(cc) do { _Pragma("unroll") for (int jj = 0; jj < 4; ++jj) gt[jj] = *(const v4u*)(Y + ((size_t)b * SEQL + 64 * (cc) + ((lt + 256 * jj) >> 4)) * 1024 + (size_t)h * 128 + 8 * foct); } while (0)
; __device__ __forceinline__ void hgrn_unit(LAS unsigned char* lds, int b, int h, const bf16* Q, const bf16* KK, const bf16* V, const bf16* PBUF, const float* DBUF, bf16* Y, const float* onw) {
;     ...
;         LD_ISSUE(0, lqA, lkA, lvA, lpA, ldA);
;         LD_WRITE(0, lqA, lkA, lvA, lpA, ldA); LD_ISSUE(1, lqA, lkA, lvA, lpA, ldA);
;         GATE_LOAD(0);
;         LBAR();
; #pragma unroll 1
;         for (int c = 0; c < 32; ++c) {
;             if (c > 0) { FINISH(c - 1); GATE_LOAD(c); }
	v_mov_b32_e32 v66, v82
	s_waitcnt lgkmcnt(0)
	v_mov_b32_e32 v67, v150
	v_mov_b32_e32 v150, v83
	v_pk_add_f32 v[82:83], v[66:67], v[150:151]
	v_add_u32_e32 v66, v147, v105
	ds_read_b128 v[66:69], v66
	v_mov_b32_e32 v150, v84
	v_mov_b32_e32 v151, v152
	v_mov_b32_e32 v152, v85
	v_pk_add_f32 v[84:85], v[150:151], v[152:153]
	v_and_b32_e32 v163, 0xffff0000, v15
	v_pk_add_f32 v[150:151], v[82:83], v[84:85]
	ds_read_b128 v[82:85], v171
	s_waitcnt lgkmcnt(1)
	v_lshlrev_b32_e32 v152, 16, v66
	v_and_b32_e32 v153, 0xffff0000, v66
	v_lshlrev_b32_e32 v158, 16, v67
	v_and_b32_e32 v159, 0xffff0000, v67
	v_lshlrev_b32_e32 v164, 16, v68
	v_and_b32_e32 v165, 0xffff0000, v68
	v_lshlrev_b32_e32 v168, 16, v69
	v_and_b32_e32 v169, 0xffff0000, v69
	ds_read_b128 v[66:69], v171 offset:16
	s_waitcnt lgkmcnt(1)
	v_mov_b32_e32 v172, v82
	v_mov_b32_e32 v82, v84
	v_lshlrev_b32_e32 v166, 16, v16
	v_and_b32_e32 v167, 0xffff0000, v16
	s_waitcnt lgkmcnt(0)
	v_mov_b32_e32 v173, v66
	v_mov_b32_e32 v66, v83
	v_mov_b32_e32 v83, v68
	v_mov_b32_e32 v68, v85
	v_pk_add_f32 v[66:67], v[172:173], v[66:67]
	v_pk_add_f32 v[68:69], v[82:83], v[68:69]
	v_add_u32_e32 v14, v147, v97
	v_pk_add_f32 v[66:67], v[66:67], v[68:69]
	v_mov_b32_e32 v69, v150
	v_mov_b32_e32 v68, v66
	v_mov_b32_e32 v150, v67
	v_pk_add_f32 v[66:67], v[68:69], v[150:151]
	v_lshlrev_b32_e32 v170, 16, v17
	v_pk_fma_f32 v[82:83], v[66:67], s[22:23], v[154:155] op_sel_hi:[1,0,0]
	v_and_b32_e32 v171, 0xffff0000, v17
	ds_read_b128 v[14:17], v14
	s_nop 0
	v_mov_b32_e32 v66, v83
	v_rsq_f32_e32 v68, v66
	v_lshl_add_u64 v[66:67], s[8:9], 0, v[88:89]
	v_lshlrev_b64 v[66:67], 11, v[66:67]
	v_lshl_add_u64 v[84:85], v[110:111], 0, v[66:67]
	s_nop 0
	v_mov_b32_e32 v150, v68
	v_pk_mul_f32 v[66:67], v[150:151], v[152:153] op_sel_hi:[0,1]
	v_pk_mul_f32 v[68:69], v[150:151], v[158:159] op_sel_hi:[0,1]
	v_pk_mul_f32 v[66:67], v[6:7], v[66:67]
	v_pk_mul_f32 v[68:69], v[8:9], v[68:69]
	v_pk_mul_f32 v[66:67], v[66:67], v[156:157]
	v_pk_mul_f32 v[68:69], v[68:69], v[162:163]
	v_cvt_pk_bf16_f32 v66, v66, v67
	v_cvt_pk_bf16_f32 v67, v68, v69
	v_pk_mul_f32 v[68:69], v[150:151], v[164:165] op_sel_hi:[0,1]
	v_pk_mul_f32 v[68:69], v[2:3], v[68:69]
	v_pk_mul_f32 v[68:69], v[68:69], v[166:167]
	v_pk_mul_f32 v[150:151], v[150:151], v[168:169] op_sel_hi:[0,1]
	v_cvt_pk_bf16_f32 v68, v68, v69
	v_mov_b32_e32 v69, v82
	v_rsq_f32_e32 v147, v69
	v_pk_mul_f32 v[150:151], v[4:5], v[150:151]
	s_nop 0
	v_pk_mul_f32 v[82:83], v[150:151], v[170:171]
	s_nop 0
	v_cvt_pk_bf16_f32 v69, v82, v83
	global_store_dwordx4 v[84:85], v[66:69], off nt
	s_waitcnt vmcnt(17)
	v_lshlrev_b32_e32 v82, 16, v10
	v_and_b32_e32 v83, 0xffff0000, v10
	s_nop 0
	v_mov_b32_e32 v66, v147
	s_waitcnt lgkmcnt(0)
	v_lshlrev_b32_e32 v68, 16, v14
	v_and_b32_e32 v69, 0xffff0000, v14
	v_pk_mul_f32 v[68:69], v[66:67], v[68:69] op_sel_hi:[0,1]
	v_pk_mul_f32 v[68:69], v[6:7], v[68:69]
	v_lshlrev_b32_e32 v14, 16, v15
	v_and_b32_e32 v15, 0xffff0000, v15
	v_pk_mul_f32 v[68:69], v[68:69], v[82:83]
	v_pk_mul_f32 v[14:15], v[66:67], v[14:15] op_sel_hi:[0,1]
	v_cvt_pk_bf16_f32 v10, v68, v69
	v_pk_mul_f32 v[14:15], v[8:9], v[14:15]
	v_lshlrev_b32_e32 v68, 16, v11
	v_and_b32_e32 v69, 0xffff0000, v11
	v_pk_mul_f32 v[14:15], v[14:15], v[68:69]
	v_lshlrev_b32_e32 v68, 16, v12
	v_cvt_pk_bf16_f32 v11, v14, v15
	v_lshlrev_b32_e32 v14, 16, v16
	v_and_b32_e32 v15, 0xffff0000, v16
	v_pk_mul_f32 v[14:15], v[66:67], v[14:15] op_sel_hi:[0,1]
	v_pk_mul_f32 v[14:15], v[2:3], v[14:15]
	v_and_b32_e32 v69, 0xffff0000, v12
	v_pk_mul_f32 v[14:15], v[14:15], v[68:69]
	v_lshlrev_b32_e32 v16, 16, v13
	v_cvt_pk_bf16_f32 v12, v14, v15
	v_lshlrev_b32_e32 v14, 16, v17
	v_and_b32_e32 v15, 0xffff0000, v17
	v_pk_mul_f32 v[14:15], v[66:67], v[14:15] op_sel_hi:[0,1]
	v_pk_mul_f32 v[14:15], v[4:5], v[14:15]
	v_and_b32_e32 v17, 0xffff0000, v13
	v_pk_mul_f32 v[14:15], v[14:15], v[16:17]
	s_nop 0
	v_cvt_pk_bf16_f32 v13, v14, v15
	v_lshl_add_u64 v[14:15], s[8:9], 0, v[86:87]
	v_lshlrev_b64 v[14:15], 11, v[14:15]
	v_lshl_add_u64 v[14:15], v[110:111], 0, v[14:15]
	global_store_dwordx4 v[14:15], v[10:13], off nt
	s_nop 1
	v_lshl_add_u64 v[10:11], v[128:129], 0, s[6:7]
	v_lshl_add_u64 v[12:13], v[126:127], 0, s[6:7]
	global_load_dwordx4 v[82:85], v[10:11], off
	global_load_dwordx4 v[66:69], v[12:13], off
	v_lshl_add_u64 v[10:11], v[124:125], 0, s[6:7]
	v_lshl_add_u64 v[12:13], v[122:123], 0, s[6:7]
	global_load_dwordx4 v[14:17], v[10:11], off
	s_nop 0
	global_load_dwordx4 v[10:13], v[12:13], off

; #define LBAR() do { asm volatile("s_waitcnt lgkmcnt(0)" ::: "memory"); __builtin_amdgcn_s_barrier(); asm volatile("" ::: "memory"); } while (0)
; #define GATE_LOAD(cc) do { _Pragma("unroll") for (int jj = 0; jj < 4; ++jj) gt[jj] = *(const v4u*)(Y + ((size_t)b * SEQL + 64 * (cc) + ((lt + 256 * jj) >> 4)) * 1024 + (size_t)h * 128 + 8 * foct); } while (0)
; __device__ __forceinline__ void hgrn_unit(LAS unsigned char* lds, int b, int h, const bf16* Q, const bf16* KK, const bf16* V, const bf16* PBUF, const float* DBUF, bf16* Y, const float* onw) {
;     ...
;         LD_ISSUE(0, lqA, lkA, lvA, lpA, ldA);
;         LD_WRITE(0, lqA, lkA, lvA, lpA, ldA); LD_ISSUE(1, lqA, lkA, lvA, lpA, ldA);
;         GATE_LOAD(0);
;         LBAR();
; #pragma unroll 1
;         for (int c = 0; c < 32; ++c) {
;             if (c > 0) { FINISH(c - 1); GATE_LOAD(c); }
;             if (c + 1 < 32) { LD_WRITE((c + 1) & 1, lqA, lkA, lvA, lpA, ldA); if (c + 2 < 32) LD_ISSUE(c + 2, lqA, lkA, lvA, lpA, ldA); }
;             LBAR();
;         }
;         FINISH(31);
.LBB0_1304:
	s_waitcnt vmcnt(8)
	v_readlane_b32 s1, v255, 0
	v_readlane_b32 s0, v254, 63
	s_or_b32 s2, s2, 0x7c0
	s_waitcnt vmcnt(12)
	v_add_u32_e32 v22, s1, v136
	ds_read_b128 v[18:21], v22
	ds_read_b128 v[22:25], v22 offset:16
	s_waitcnt vmcnt(5)
	v_lshl_add_u32 v50, v96, 1, s0
	s_mov_b32 s0, 0x358637bd
	s_waitcnt vmcnt(3)
	v_lshlrev_b32_e32 v34, 16, v82
	s_waitcnt lgkmcnt(1)
	v_mov_b32_e32 v26, v18
	s_waitcnt lgkmcnt(0)
	v_mov_b32_e32 v27, v22
	v_mov_b32_e32 v22, v19
	v_add_u32_e32 v18, v50, v134
	v_pk_add_f32 v[22:23], v[26:27], v[22:23]
	v_mov_b32_e32 v26, v20
	v_mov_b32_e32 v27, v24
	v_mov_b32_e32 v24, v21
	ds_read_b128 v[18:21], v18
	v_pk_add_f32 v[24:25], v[26:27], v[24:25]
	v_add_u32_e32 v26, s1, v133
	v_pk_add_f32 v[30:31], v[22:23], v[24:25]
	ds_read_b128 v[22:25], v26
	s_waitcnt lgkmcnt(1)
	v_lshlrev_b32_e32 v32, 16, v18
	v_and_b32_e32 v33, 0xffff0000, v18
	v_lshlrev_b32_e32 v36, 16, v19
	v_and_b32_e32 v37, 0xffff0000, v19
	v_lshlrev_b32_e32 v40, 16, v20
	v_and_b32_e32 v41, 0xffff0000, v20
	v_lshlrev_b32_e32 v44, 16, v21
	v_and_b32_e32 v45, 0xffff0000, v21
	ds_read_b128 v[18:21], v26 offset:16
	s_waitcnt lgkmcnt(1)
	v_mov_b32_e32 v48, v22
	v_add_u32_e32 v22, v50, v132
	ds_read_b128 v[26:29], v22
	v_mov_b32_e32 v22, v24
	s_waitcnt lgkmcnt(1)
	v_mov_b32_e32 v49, v18
	v_mov_b32_e32 v18, v23
	v_mov_b32_e32 v23, v20
	v_mov_b32_e32 v20, v25
	v_pk_add_f32 v[18:19], v[48:49], v[18:19]
	v_pk_add_f32 v[20:21], v[22:23], v[20:21]
	v_and_b32_e32 v35, 0xffff0000, v82
	v_pk_add_f32 v[18:19], v[18:19], v[20:21]
	v_mov_b32_e32 v21, v30
	v_mov_b32_e32 v20, v18
	v_mov_b32_e32 v30, v19
	v_pk_add_f32 v[18:19], v[20:21], v[30:31]
	v_mov_b64_e32 v[30:31], s[0:1]
	s_brev_b32 s0, 60
	v_pk_fma_f32 v[22:23], v[18:19], s[0:1], v[30:31] op_sel_hi:[1,0,0]
	v_lshlrev_b32_e32 v38, 16, v83
	v_and_b32_e32 v39, 0xffff0000, v83
	v_lshlrev_b32_e32 v42, 16, v84
	v_mov_b32_e32 v18, v23
	v_rsq_f32_e32 v20, v18
	v_lshl_add_u64 v[18:19], s[2:3], 0, v[92:93]
	v_lshlrev_b64 v[18:19], 11, v[18:19]
	v_lshl_add_u64 v[24:25], v[94:95], 0, v[18:19]
	s_nop 0
	v_mov_b32_e32 v48, v20
	v_pk_mul_f32 v[18:19], v[48:49], v[32:33] op_sel_hi:[0,1]
	v_pk_mul_f32 v[20:21], v[48:49], v[36:37] op_sel_hi:[0,1]
	v_pk_mul_f32 v[18:19], v[6:7], v[18:19]
	v_pk_mul_f32 v[20:21], v[8:9], v[20:21]
	v_pk_mul_f32 v[18:19], v[18:19], v[34:35]
	v_pk_mul_f32 v[20:21], v[20:21], v[38:39]
	v_cvt_pk_bf16_f32 v18, v18, v19
	v_cvt_pk_bf16_f32 v19, v20, v21
	v_pk_mul_f32 v[20:21], v[48:49], v[40:41] op_sel_hi:[0,1]
	v_and_b32_e32 v43, 0xffff0000, v84
	v_pk_mul_f32 v[20:21], v[2:3], v[20:21]
	v_pk_mul_f32 v[20:21], v[20:21], v[42:43]
	v_pk_mul_f32 v[32:33], v[48:49], v[44:45] op_sel_hi:[0,1]
	v_cvt_pk_bf16_f32 v20, v20, v21
	v_mov_b32_e32 v21, v22
	v_rsq_f32_e32 v34, v21
	v_lshlrev_b32_e32 v46, 16, v85
	v_and_b32_e32 v47, 0xffff0000, v85
	v_pk_mul_f32 v[32:33], v[4:5], v[32:33]
	v_add_u32_e32 v45, s1, v103
	v_pk_mul_f32 v[22:23], v[32:33], v[46:47]
	v_lshl_add_u64 v[32:33], s[2:3], 0, v[90:91]
	v_cvt_pk_bf16_f32 v21, v22, v23
	global_store_dwordx4 v[24:25], v[18:21], off nt
	s_waitcnt vmcnt(3)
	v_lshlrev_b32_e32 v24, 16, v67
	v_and_b32_e32 v25, 0xffff0000, v67
	s_nop 0
	v_mov_b32_e32 v22, v34
	s_waitcnt lgkmcnt(0)
	v_lshlrev_b32_e32 v18, 16, v26
	v_and_b32_e32 v19, 0xffff0000, v26
	v_pk_mul_f32 v[18:19], v[22:23], v[18:19] op_sel_hi:[0,1]
	v_pk_mul_f32 v[18:19], v[6:7], v[18:19]
	v_lshlrev_b32_e32 v20, 16, v66
	v_and_b32_e32 v21, 0xffff0000, v66
	v_pk_mul_f32 v[18:19], v[18:19], v[20:21]
	v_lshlrev_b32_e32 v20, 16, v27
	v_and_b32_e32 v21, 0xffff0000, v27
	v_pk_mul_f32 v[20:21], v[22:23], v[20:21] op_sel_hi:[0,1]
	v_pk_mul_f32 v[20:21], v[8:9], v[20:21]
	v_cvt_pk_bf16_f32 v18, v18, v19
	v_pk_mul_f32 v[20:21], v[20:21], v[24:25]
	v_lshlrev_b32_e32 v24, 16, v68
	v_cvt_pk_bf16_f32 v19, v20, v21
	v_lshlrev_b32_e32 v20, 16, v28
	v_and_b32_e32 v21, 0xffff0000, v28
	v_pk_mul_f32 v[20:21], v[22:23], v[20:21] op_sel_hi:[0,1]
	v_pk_mul_f32 v[20:21], v[2:3], v[20:21]
	v_and_b32_e32 v25, 0xffff0000, v68
	v_pk_mul_f32 v[20:21], v[20:21], v[24:25]
	v_lshlrev_b32_e32 v24, 16, v29
	v_and_b32_e32 v25, 0xffff0000, v29
	v_pk_mul_f32 v[22:23], v[22:23], v[24:25] op_sel_hi:[0,1]
	v_pk_mul_f32 v[22:23], v[4:5], v[22:23]
	v_lshlrev_b32_e32 v24, 16, v69
	v_and_b32_e32 v25, 0xffff0000, v69
	v_pk_mul_f32 v[22:23], v[22:23], v[24:25]
	v_add_u32_e32 v26, s1, v107
	v_cvt_pk_bf16_f32 v20, v20, v21
	v_cvt_pk_bf16_f32 v21, v22, v23
	ds_read_b128 v[22:25], v26
	ds_read_b128 v[26:29], v26 offset:16
	v_lshlrev_b64 v[32:33], 11, v[32:33]
	v_lshl_add_u64 v[32:33], v[94:95], 0, v[32:33]
	global_store_dwordx4 v[32:33], v[18:21], off nt
	s_waitcnt vmcnt(3)
	v_lshlrev_b32_e32 v32, 16, v14
	v_and_b32_e32 v33, 0xffff0000, v14
	s_waitcnt lgkmcnt(1)
	v_mov_b32_e32 v18, v22
	s_waitcnt lgkmcnt(0)
	v_mov_b32_e32 v19, v26
	v_mov_b32_e32 v26, v23
	v_pk_add_f32 v[22:23], v[18:19], v[26:27]
	v_add_u32_e32 v18, v50, v105
	ds_read_b128 v[18:21], v18
	v_mov_b32_e32 v26, v24
	v_mov_b32_e32 v27, v28
	v_mov_b32_e32 v28, v25
	v_pk_add_f32 v[24:25], v[26:27], v[28:29]
	v_lshlrev_b32_e32 v36, 16, v15
	v_pk_add_f32 v[26:27], v[22:23], v[24:25]
	ds_read_b128 v[22:25], v45
	s_waitcnt lgkmcnt(1)
	v_lshlrev_b32_e32 v28, 16, v18
	v_and_b32_e32 v29, 0xffff0000, v18
	v_lshlrev_b32_e32 v34, 16, v19
	v_and_b32_e32 v35, 0xffff0000, v19
	v_lshlrev_b32_e32 v38, 16, v20
	v_and_b32_e32 v39, 0xffff0000, v20
	v_lshlrev_b32_e32 v42, 16, v21
	v_and_b32_e32 v43, 0xffff0000, v21
	ds_read_b128 v[18:21], v45 offset:16
	s_waitcnt lgkmcnt(1)
	v_mov_b32_e32 v46, v22
	v_mov_b32_e32 v22, v24
	v_and_b32_e32 v37, 0xffff0000, v15
	v_lshlrev_b32_e32 v40, 16, v16
	s_waitcnt lgkmcnt(0)
	v_mov_b32_e32 v47, v18
	v_mov_b32_e32 v18, v23
	v_mov_b32_e32 v23, v20
	v_mov_b32_e32 v20, v25
	v_pk_add_f32 v[18:19], v[46:47], v[18:19]
	v_pk_add_f32 v[20:21], v[22:23], v[20:21]
	v_and_b32_e32 v41, 0xffff0000, v16
	v_pk_add_f32 v[18:19], v[18:19], v[20:21]
	v_mov_b32_e32 v21, v26
	v_mov_b32_e32 v20, v18
	v_mov_b32_e32 v26, v19
	v_pk_add_f32 v[18:19], v[20:21], v[26:27]
	v_add_u32_e32 v14, v50, v97
	v_pk_fma_f32 v[22:23], v[18:19], s[0:1], v[30:31] op_sel_hi:[1,0,0]
	v_lshlrev_b32_e32 v44, 16, v17
	v_and_b32_e32 v45, 0xffff0000, v17
	ds_read_b128 v[14:17], v14
	v_mov_b32_e32 v18, v23
	v_rsq_f32_e32 v20, v18
	v_lshl_add_u64 v[18:19], s[2:3], 0, v[88:89]
	v_lshlrev_b64 v[18:19], 11, v[18:19]
	v_lshl_add_u64 v[24:25], v[94:95], 0, v[18:19]
	s_nop 0
	v_mov_b32_e32 v26, v20
	v_pk_mul_f32 v[18:19], v[26:27], v[28:29] op_sel_hi:[0,1]
	v_pk_mul_f32 v[20:21], v[26:27], v[34:35] op_sel_hi:[0,1]
	v_pk_mul_f32 v[18:19], v[6:7], v[18:19]
	v_pk_mul_f32 v[20:21], v[8:9], v[20:21]
	v_pk_mul_f32 v[18:19], v[18:19], v[32:33]
	v_pk_mul_f32 v[20:21], v[20:21], v[36:37]
	v_cvt_pk_bf16_f32 v18, v18, v19
	v_cvt_pk_bf16_f32 v19, v20, v21
	v_pk_mul_f32 v[20:21], v[26:27], v[38:39] op_sel_hi:[0,1]
	v_pk_mul_f32 v[20:21], v[2:3], v[20:21]
	v_pk_mul_f32 v[20:21], v[20:21], v[40:41]
	v_pk_mul_f32 v[26:27], v[26:27], v[42:43] op_sel_hi:[0,1]
	v_cvt_pk_bf16_f32 v20, v20, v21
	v_mov_b32_e32 v21, v22
	v_rsq_f32_e32 v28, v21
	v_pk_mul_f32 v[26:27], v[4:5], v[26:27]
	s_mov_b64 s[0:1], 0
	v_pk_mul_f32 v[22:23], v[26:27], v[44:45]
	s_nop 0
	v_cvt_pk_bf16_f32 v21, v22, v23
	global_store_dwordx4 v[24:25], v[18:21], off nt
	s_nop 1
	s_nop 0
	v_mov_b32_e32 v18, v28
	s_waitcnt lgkmcnt(0)
	v_lshlrev_b32_e32 v20, 16, v14
	v_and_b32_e32 v21, 0xffff0000, v14
	v_lshlrev_b32_e32 v14, 16, v15
	v_and_b32_e32 v15, 0xffff0000, v15
	v_pk_mul_f32 v[20:21], v[18:19], v[20:21] op_sel_hi:[0,1]
	v_pk_mul_f32 v[14:15], v[18:19], v[14:15] op_sel_hi:[0,1]
	v_pk_mul_f32 v[6:7], v[6:7], v[20:21]
	s_waitcnt vmcnt(3)
	v_lshlrev_b32_e32 v20, 16, v10
	v_and_b32_e32 v21, 0xffff0000, v10
	v_pk_mul_f32 v[8:9], v[8:9], v[14:15]
	v_lshlrev_b32_e32 v10, 16, v11
	v_and_b32_e32 v11, 0xffff0000, v11
	v_pk_mul_f32 v[6:7], v[6:7], v[20:21]
	v_pk_mul_f32 v[8:9], v[8:9], v[10:11]
	v_cvt_pk_bf16_f32 v6, v6, v7
	v_cvt_pk_bf16_f32 v7, v8, v9
	v_lshlrev_b32_e32 v8, 16, v16
	v_and_b32_e32 v9, 0xffff0000, v16
	v_pk_mul_f32 v[8:9], v[18:19], v[8:9] op_sel_hi:[0,1]
	v_pk_mul_f32 v[2:3], v[2:3], v[8:9]
	v_lshlrev_b32_e32 v8, 16, v12
	v_and_b32_e32 v9, 0xffff0000, v12
	v_pk_mul_f32 v[2:3], v[2:3], v[8:9]
	s_nop 0
	v_cvt_pk_bf16_f32 v8, v2, v3
	v_lshlrev_b32_e32 v2, 16, v17
	v_and_b32_e32 v3, 0xffff0000, v17
	v_pk_mul_f32 v[2:3], v[18:19], v[2:3] op_sel_hi:[0,1]
	v_pk_mul_f32 v[2:3], v[4:5], v[2:3]
	v_lshlrev_b32_e32 v4, 16, v13
	v_and_b32_e32 v5, 0xffff0000, v13
	v_pk_mul_f32 v[2:3], v[2:3], v[4:5]
	s_nop 0
	v_cvt_pk_bf16_f32 v9, v2, v3
	v_lshl_add_u64 v[2:3], s[2:3], 0, v[86:87]
	v_lshlrev_b64 v[2:3], 11, v[2:3]
	v_lshl_add_u64 v[2:3], v[94:95], 0, v[2:3]
	global_store_dwordx4 v[2:3], v[6:9], off nt
	s_setprio 0
